# as v24 plus EpiQRope rope-table loads hoisted per half under the rope-lane mask, final norm loop loads issued one row ahead
# speedup vs baseline: 1.0118x; 1.0031x over previous
; __device__ __forceinline__ unsigned cvt_pk_bf16(float lo, float hi) { unsigned r; asm volatile("v_cvt_pk_bf16_f32 %0, %1, %2" : "=v"(r) : "v"(lo), "v"(hi)); return r; }
;     __device__ __forceinline__ void operator()(const f32x4 (&acc)[2][2][4][2], const Unit& u, int wr, int wc, int fr, int fq, const float (&rs)[2][4]) const {
;     ...
;             const int cb = u.pn * BM + bj * HALF + wc * 32 + 8 * fq; const int d = cb % 96; const bool rope = d >= 64; const int i0 = rope ? ((d - 64) >> 1) : 0;
; #pragma unroll
;             for (int ai = 0; ai < 2; ++ai)
; #pragma unroll
;                 for (int m = 0; m < 4; ++m) { const int row = row0 + ai * HALF + m * 16; f32x4 v0 = acc[ai][bj][m][0], v1 = acc[ai][bj][m][1];
;                     if (rope) { const float* cs = tab + ((size_t)(row & pmask) * 16 + i0) * 2; const f32x4 c01 = *(const f32x4*)cs, c23 = *(const f32x4*)(cs + 4);
;                         const f32x4 a = v0, b = v1;
;                         v0[0] = a[0] * c01[0] - a[1] * c01[1]; v0[1] = a[0] * c01[1] + a[1] * c01[0];
;                         v0[2] = a[2] * c01[2] - a[3] * c01[3]; v0[3] = a[2] * c01[3] + a[3] * c01[2];
;                         v1[0] = b[0] * c23[0] - b[1] * c23[1]; v1[1] = b[0] * c23[1] + b[1] * c23[0];
;                         v1[2] = b[2] * c23[2] - b[3] * c23[3]; v1[3] = b[2] * c23[3] + b[3] * c23[2]; }
;                     u32x4 w; w.x = cvt_pk_bf16(v0[0], v0[1]); w.y = cvt_pk_bf16(v0[2], v0[3]); w.z = cvt_pk_bf16(v1[0], v1[1]); w.w = cvt_pk_bf16(v1[2], v1[3]);
;                     *(u32x4*)(O + (size_t)row * 768 + cb) = w;
.LBB0_1760:
	s_lshl_b32 s0, s25, 8
	v_mov_b32_e32 v80, v154
	v_mov_b32_e32 v130, v155
	s_add_i32 s0, s0, s66
	s_cmp_lt_i32 s25, 64
	v_add_u32_e32 v158, s0, v80
	s_movk_i32 s0, 0x1fff
	s_cselect_b32 s25, s0, 0xfff
	s_lshl_b32 s0, s24, 8
	s_or_b32 s0, s0, s67
	v_lshl_add_u32 v148, v130, 3, s0
	s_mov_b32 s0, 0x2aaaaaab
	v_mul_hi_i32 v80, v148, s0
	v_lshrrev_b32_e32 v130, 31, v80
	v_lshrrev_b32_e32 v80, 4, v80
	v_add_u32_e32 v80, v80, v130
	v_mul_lo_u32 v80, v80, s83
	v_sub_u32_e32 v80, v148, v80
	v_cmp_lt_i32_e32 vcc, 63, v80
	v_subrev_u32_e32 v80, 64, v80
	v_ashrrev_i32_e32 v150, 1, v80
	v_and_b32_e32 v80, s25, v158
	v_ashrrev_i32_e32 v151, 31, v150
	v_lshlrev_b32_e32 v80, 4, v80
	s_and_saveexec_b64 s[48:49], vcc
	s_cbranch_execz .Lqr_h0
	v_and_b32_e32 v250, s25, v158
	v_lshlrev_b32_e32 v250, 4, v250
	v_mov_b32_e32 v251, v81
	v_lshl_add_u64 v[250:251], v[150:151], 0, v[250:251]
	v_lshl_add_u64 v[250:251], v[250:251], 3, s[78:79]
	global_load_dwordx4 v[186:189], v[250:251], off offset:16
	global_load_dwordx4 v[190:193], v[250:251], off
	v_add_u32_e32 v250, 16, v158
	v_and_b32_e32 v250, s25, v250
	v_lshlrev_b32_e32 v250, 4, v250
	v_mov_b32_e32 v251, v81
	v_lshl_add_u64 v[250:251], v[150:151], 0, v[250:251]
	v_lshl_add_u64 v[250:251], v[250:251], 3, s[78:79]
	global_load_dwordx4 v[194:197], v[250:251], off offset:16
	global_load_dwordx4 v[198:201], v[250:251], off
	v_add_u32_e32 v250, 32, v158
	v_and_b32_e32 v250, s25, v250
	v_lshlrev_b32_e32 v250, 4, v250
	v_mov_b32_e32 v251, v81
	v_lshl_add_u64 v[250:251], v[150:151], 0, v[250:251]
	v_lshl_add_u64 v[250:251], v[250:251], 3, s[78:79]
	global_load_dwordx4 v[202:205], v[250:251], off offset:16
	global_load_dwordx4 v[206:209], v[250:251], off
	v_add_u32_e32 v250, 48, v158
	v_and_b32_e32 v250, s25, v250
	v_lshlrev_b32_e32 v250, 4, v250
	v_mov_b32_e32 v251, v81
	v_lshl_add_u64 v[250:251], v[150:151], 0, v[250:251]
	v_lshl_add_u64 v[250:251], v[250:251], 3, s[78:79]
	global_load_dwordx4 v[210:213], v[250:251], off offset:16
	global_load_dwordx4 v[214:217], v[250:251], off
	v_add_u32_e32 v250, 0x80, v158
	v_and_b32_e32 v250, s25, v250
	v_lshlrev_b32_e32 v250, 4, v250
	v_mov_b32_e32 v251, v81
	v_lshl_add_u64 v[250:251], v[150:151], 0, v[250:251]
	v_lshl_add_u64 v[250:251], v[250:251], 3, s[78:79]
	global_load_dwordx4 v[218:221], v[250:251], off offset:16
	global_load_dwordx4 v[222:225], v[250:251], off
	v_add_u32_e32 v250, 0x90, v158
	v_and_b32_e32 v250, s25, v250
	v_lshlrev_b32_e32 v250, 4, v250
	v_mov_b32_e32 v251, v81
	v_lshl_add_u64 v[250:251], v[150:151], 0, v[250:251]
	v_lshl_add_u64 v[250:251], v[250:251], 3, s[78:79]
	global_load_dwordx4 v[226:229], v[250:251], off offset:16
	global_load_dwordx4 v[230:233], v[250:251], off
	v_add_u32_e32 v250, 0xa0, v158
	v_and_b32_e32 v250, s25, v250
	v_lshlrev_b32_e32 v250, 4, v250
	v_mov_b32_e32 v251, v81
	v_lshl_add_u64 v[250:251], v[150:151], 0, v[250:251]
	v_lshl_add_u64 v[250:251], v[250:251], 3, s[78:79]
	global_load_dwordx4 v[234:237], v[250:251], off offset:16
	global_load_dwordx4 v[238:241], v[250:251], off
	v_add_u32_e32 v250, 0xb0, v158
	v_and_b32_e32 v250, s25, v250
	v_lshlrev_b32_e32 v250, 4, v250
	v_mov_b32_e32 v251, v81
	v_lshl_add_u64 v[250:251], v[150:151], 0, v[250:251]
	v_lshl_add_u64 v[250:251], v[250:251], 3, s[78:79]
	global_load_dwordx4 v[242:245], v[250:251], off offset:16
	global_load_dwordx4 v[246:249], v[250:251], off
	s_waitcnt vmcnt(0)
.Lqr_h0:
	s_or_b64 exec, exec, s[48:49]
	s_and_saveexec_b64 s[48:49], vcc
	s_cbranch_execz .LBB0_1762
	v_lshl_add_u64 v[152:153], v[150:151], 0, v[80:81]
	v_lshl_add_u64 v[152:153], v[152:153], 3, s[78:79]
	v_pk_mul_f32 v[172:173], v[122:123], v[186:187] op_sel:[1,1] op_sel_hi:[1,0]
	v_pk_mul_f32 v[164:165], v[126:127], v[190:191] op_sel:[1,1] op_sel_hi:[1,0]
	v_pk_mul_f32 v[152:153], v[126:127], v[190:191]
	v_pk_fma_f32 v[126:127], v[126:127], v[190:191], v[164:165] op_sel_hi:[0,1,1]
	v_mul_f32_e32 v126, v129, v193
	v_pk_fma_f32 v[168:169], v[128:129], v[192:193], v[126:127] op_sel_hi:[1,1,0] neg_lo:[0,0,1] neg_hi:[0,0,1]
	v_mul_f32_e32 v126, v129, v192
	v_pk_fma_f32 v[170:171], v[128:129], v[192:193], v[126:127] op_sel:[0,1,0] op_sel_hi:[1,0,0]
	v_pk_mul_f32 v[128:129], v[122:123], v[186:187]
	v_pk_fma_f32 v[122:123], v[122:123], v[186:187], v[172:173] op_sel_hi:[0,1,1]
	v_mul_f32_e32 v122, v125, v189
	v_pk_fma_f32 v[160:161], v[124:125], v[188:189], v[122:123] op_sel_hi:[1,1,0] neg_lo:[0,0,1] neg_hi:[0,0,1]
	v_mul_f32_e32 v122, v125, v188
	v_pk_fma_f32 v[162:163], v[124:125], v[188:189], v[122:123] op_sel:[0,1,0] op_sel_hi:[1,0,0]
	v_sub_f32_e32 v126, v152, v164
	v_sub_f32_e32 v122, v128, v172
	v_mov_b32_e32 v128, v168
	v_mov_b32_e32 v129, v170
	v_mov_b32_e32 v124, v160
	v_mov_b32_e32 v125, v162
.LBB0_1762:
	s_or_b64 exec, exec, s[48:49]
	v_ashrrev_i32_e32 v149, 31, v148
	v_lshl_add_u64 v[152:153], v[148:149], 1, s[56:57]
	v_cvt_pk_bf16_f32 v126, v126, v127
	v_cvt_pk_bf16_f32 v127, v128, v129
	v_cvt_pk_bf16_f32 v128, v122, v123
	v_mad_i64_i32 v[122:123], s[0:1], v158, s91, v[152:153]
	v_cvt_pk_bf16_f32 v129, v124, v125
	global_store_dwordx4 v[122:123], v[126:129], off
	v_add_u32_e32 v124, 16, v158
	v_and_b32_e32 v122, s25, v124
	v_lshlrev_b32_e32 v122, 4, v122
	s_and_saveexec_b64 s[48:49], vcc
	s_cbranch_execz .LBB0_1764
	v_mov_b32_e32 v123, v81
	v_lshl_add_u64 v[126:127], v[150:151], 0, v[122:123]
	v_lshl_add_u64 v[160:161], v[126:127], 3, s[78:79]
	s_nop 0
	v_pk_mul_f32 v[170:171], v[114:115], v[194:195] op_sel:[1,1] op_sel_hi:[1,0]
	v_pk_mul_f32 v[168:169], v[118:119], v[198:199] op_sel:[1,1] op_sel_hi:[1,0]
	v_pk_mul_f32 v[164:165], v[118:119], v[198:199]
	v_pk_fma_f32 v[118:119], v[118:119], v[198:199], v[168:169] op_sel_hi:[0,1,1]
	v_mul_f32_e32 v118, v121, v201
	v_pk_fma_f32 v[160:161], v[120:121], v[200:201], v[118:119] op_sel_hi:[1,1,0] neg_lo:[0,0,1] neg_hi:[0,0,1]
	v_mul_f32_e32 v118, v121, v200
	v_pk_fma_f32 v[162:163], v[120:121], v[200:201], v[118:119] op_sel:[0,1,0] op_sel_hi:[1,0,0]
	v_pk_mul_f32 v[120:121], v[114:115], v[194:195]
	v_pk_fma_f32 v[114:115], v[114:115], v[194:195], v[170:171] op_sel_hi:[0,1,1]
	v_mul_f32_e32 v114, v117, v197
	v_pk_fma_f32 v[126:127], v[116:117], v[196:197], v[114:115] op_sel_hi:[1,1,0] neg_lo:[0,0,1] neg_hi:[0,0,1]
	v_mul_f32_e32 v114, v117, v196
	v_pk_fma_f32 v[128:129], v[116:117], v[196:197], v[114:115] op_sel:[0,1,0] op_sel_hi:[1,0,0]
	v_sub_f32_e32 v118, v164, v168
	v_sub_f32_e32 v114, v120, v170
	v_mov_b32_e32 v120, v160
	v_mov_b32_e32 v121, v162
	v_mov_b32_e32 v116, v126
	v_mov_b32_e32 v117, v128
; __device__ __forceinline__ unsigned cvt_pk_bf16(float lo, float hi) { unsigned r; asm volatile("v_cvt_pk_bf16_f32 %0, %1, %2" : "=v"(r) : "v"(lo), "v"(hi)); return r; }
;     __device__ __forceinline__ void operator()(const f32x4 (&acc)[2][2][4][2], const Unit& u, int wr, int wc, int fr, int fq, const float (&rs)[2][4]) const {
;     ...
;                 for (int m = 0; m < 4; ++m) { const int row = row0 + ai * HALF + m * 16; f32x4 v0 = acc[ai][bj][m][0], v1 = acc[ai][bj][m][1];
;                     if (rope) { const float* cs = tab + ((size_t)(row & pmask) * 16 + i0) * 2; const f32x4 c01 = *(const f32x4*)cs, c23 = *(const f32x4*)(cs + 4);
;                         const f32x4 a = v0, b = v1;
;                         v0[0] = a[0] * c01[0] - a[1] * c01[1]; v0[1] = a[0] * c01[1] + a[1] * c01[0];
;                         v0[2] = a[2] * c01[2] - a[3] * c01[3]; v0[3] = a[2] * c01[3] + a[3] * c01[2];
;                         v1[0] = b[0] * c23[0] - b[1] * c23[1]; v1[1] = b[0] * c23[1] + b[1] * c23[0];
;                         v1[2] = b[2] * c23[2] - b[3] * c23[3]; v1[3] = b[2] * c23[3] + b[3] * c23[2]; }
;                     u32x4 w; w.x = cvt_pk_bf16(v0[0], v0[1]); w.y = cvt_pk_bf16(v0[2], v0[3]); w.z = cvt_pk_bf16(v1[0], v1[1]); w.w = cvt_pk_bf16(v1[2], v1[3]);
;                     *(u32x4*)(O + (size_t)row * 768 + cb) = w;
.LBB0_1764:
	s_or_b64 exec, exec, s[48:49]
	v_cvt_pk_bf16_f32 v118, v118, v119
	v_cvt_pk_bf16_f32 v119, v120, v121
	v_cvt_pk_bf16_f32 v120, v114, v115
	v_mad_i64_i32 v[114:115], s[0:1], v124, s91, v[152:153]
	v_cvt_pk_bf16_f32 v121, v116, v117
	global_store_dwordx4 v[114:115], v[118:121], off
	v_add_u32_e32 v116, 32, v158
	v_and_b32_e32 v114, s25, v116
	v_lshlrev_b32_e32 v114, 4, v114
	s_and_saveexec_b64 s[48:49], vcc
	s_cbranch_execz .LBB0_1766
	v_mov_b32_e32 v115, v81
	v_lshl_add_u64 v[118:119], v[150:151], 0, v[114:115]
	v_lshl_add_u64 v[126:127], v[118:119], 3, s[78:79]
	s_nop 0
	v_pk_mul_f32 v[164:165], v[106:107], v[202:203] op_sel:[1,1] op_sel_hi:[1,0]
	v_pk_mul_f32 v[162:163], v[110:111], v[206:207] op_sel:[1,1] op_sel_hi:[1,0]
	v_pk_mul_f32 v[160:161], v[110:111], v[206:207]
	v_pk_fma_f32 v[110:111], v[110:111], v[206:207], v[162:163] op_sel_hi:[0,1,1]
	v_mul_f32_e32 v110, v113, v209
	v_pk_fma_f32 v[126:127], v[112:113], v[208:209], v[110:111] op_sel_hi:[1,1,0] neg_lo:[0,0,1] neg_hi:[0,0,1]
	v_mul_f32_e32 v110, v113, v208
	v_pk_fma_f32 v[128:129], v[112:113], v[208:209], v[110:111] op_sel:[0,1,0] op_sel_hi:[1,0,0]
	v_pk_mul_f32 v[112:113], v[106:107], v[202:203]
	v_pk_fma_f32 v[106:107], v[106:107], v[202:203], v[164:165] op_sel_hi:[0,1,1]
	v_mul_f32_e32 v106, v109, v205
	v_pk_fma_f32 v[118:119], v[108:109], v[204:205], v[106:107] op_sel_hi:[1,1,0] neg_lo:[0,0,1] neg_hi:[0,0,1]
	v_mul_f32_e32 v106, v109, v204
	v_pk_fma_f32 v[120:121], v[108:109], v[204:205], v[106:107] op_sel:[0,1,0] op_sel_hi:[1,0,0]
	v_sub_f32_e32 v110, v160, v162
	v_sub_f32_e32 v106, v112, v164
	v_mov_b32_e32 v112, v126
	v_mov_b32_e32 v113, v128
	v_mov_b32_e32 v108, v118
	v_mov_b32_e32 v109, v120
.LBB0_1766:
	s_or_b64 exec, exec, s[48:49]
	v_cvt_pk_bf16_f32 v110, v110, v111
	v_cvt_pk_bf16_f32 v111, v112, v113
	v_cvt_pk_bf16_f32 v112, v106, v107
	v_mad_i64_i32 v[106:107], s[0:1], v116, s91, v[152:153]
	v_cvt_pk_bf16_f32 v113, v108, v109
	global_store_dwordx4 v[106:107], v[110:113], off
	v_add_u32_e32 v108, 48, v158
	v_and_b32_e32 v106, s25, v108
	v_lshlrev_b32_e32 v106, 4, v106
	s_and_saveexec_b64 s[48:49], vcc
	s_cbranch_execz .LBB0_1768
	v_mov_b32_e32 v107, v81
	v_lshl_add_u64 v[110:111], v[150:151], 0, v[106:107]
	v_lshl_add_u64 v[118:119], v[110:111], 3, s[78:79]
	s_nop 0
	v_pk_mul_f32 v[160:161], v[98:99], v[210:211] op_sel:[1,1] op_sel_hi:[1,0]
	v_pk_mul_f32 v[128:129], v[102:103], v[214:215] op_sel:[1,1] op_sel_hi:[1,0]
	v_pk_mul_f32 v[126:127], v[102:103], v[214:215]
	v_pk_fma_f32 v[102:103], v[102:103], v[214:215], v[128:129] op_sel_hi:[0,1,1]
	v_mul_f32_e32 v102, v105, v217
	v_pk_fma_f32 v[118:119], v[104:105], v[216:217], v[102:103] op_sel_hi:[1,1,0] neg_lo:[0,0,1] neg_hi:[0,0,1]
	v_mul_f32_e32 v102, v105, v216
	v_pk_fma_f32 v[120:121], v[104:105], v[216:217], v[102:103] op_sel:[0,1,0] op_sel_hi:[1,0,0]
	v_pk_mul_f32 v[104:105], v[98:99], v[210:211]
	v_pk_fma_f32 v[98:99], v[98:99], v[210:211], v[160:161] op_sel_hi:[0,1,1]
	v_mul_f32_e32 v98, v101, v213
	v_pk_fma_f32 v[110:111], v[100:101], v[212:213], v[98:99] op_sel_hi:[1,1,0] neg_lo:[0,0,1] neg_hi:[0,0,1]
	v_mul_f32_e32 v98, v101, v212
	v_pk_fma_f32 v[112:113], v[100:101], v[212:213], v[98:99] op_sel:[0,1,0] op_sel_hi:[1,0,0]
	v_sub_f32_e32 v102, v126, v128
	v_sub_f32_e32 v98, v104, v160
	v_mov_b32_e32 v104, v118
	v_mov_b32_e32 v105, v120
	v_mov_b32_e32 v100, v110
	v_mov_b32_e32 v101, v112
.LBB0_1768:
	s_or_b64 exec, exec, s[48:49]
	v_cvt_pk_bf16_f32 v102, v102, v103
	v_cvt_pk_bf16_f32 v103, v104, v105
	v_cvt_pk_bf16_f32 v104, v98, v99
	v_mad_i64_i32 v[98:99], s[0:1], v108, s91, v[152:153]
	v_cvt_pk_bf16_f32 v105, v100, v101
	global_store_dwordx4 v[98:99], v[102:105], off
	v_add_u32_e32 v100, 0x80, v158
	v_and_b32_e32 v98, s25, v100
	v_lshlrev_b32_e32 v98, 4, v98
	s_and_saveexec_b64 s[48:49], vcc
	s_cbranch_execz .LBB0_1770
	v_mov_b32_e32 v99, v81
	v_lshl_add_u64 v[102:103], v[150:151], 0, v[98:99]
	v_lshl_add_u64 v[110:111], v[102:103], 3, s[78:79]
	s_nop 0
	v_pk_mul_f32 v[126:127], v[90:91], v[218:219] op_sel:[1,1] op_sel_hi:[1,0]
	v_pk_mul_f32 v[120:121], v[94:95], v[222:223] op_sel:[1,1] op_sel_hi:[1,0]
	v_pk_mul_f32 v[118:119], v[94:95], v[222:223]
	v_pk_fma_f32 v[94:95], v[94:95], v[222:223], v[120:121] op_sel_hi:[0,1,1]
	v_mul_f32_e32 v94, v97, v225
	v_pk_fma_f32 v[110:111], v[96:97], v[224:225], v[94:95] op_sel_hi:[1,1,0] neg_lo:[0,0,1] neg_hi:[0,0,1]
	v_mul_f32_e32 v94, v97, v224
	v_pk_fma_f32 v[112:113], v[96:97], v[224:225], v[94:95] op_sel:[0,1,0] op_sel_hi:[1,0,0]
	v_pk_mul_f32 v[96:97], v[90:91], v[218:219]
	v_pk_fma_f32 v[90:91], v[90:91], v[218:219], v[126:127] op_sel_hi:[0,1,1]
	v_mul_f32_e32 v90, v93, v221
	v_pk_fma_f32 v[102:103], v[92:93], v[220:221], v[90:91] op_sel_hi:[1,1,0] neg_lo:[0,0,1] neg_hi:[0,0,1]
	v_mul_f32_e32 v90, v93, v220
	v_pk_fma_f32 v[104:105], v[92:93], v[220:221], v[90:91] op_sel:[0,1,0] op_sel_hi:[1,0,0]
	v_sub_f32_e32 v94, v118, v120
	v_sub_f32_e32 v90, v96, v126
	v_mov_b32_e32 v96, v110
	v_mov_b32_e32 v97, v112
	v_mov_b32_e32 v92, v102
	v_mov_b32_e32 v93, v104
; __device__ __forceinline__ unsigned cvt_pk_bf16(float lo, float hi) { unsigned r; asm volatile("v_cvt_pk_bf16_f32 %0, %1, %2" : "=v"(r) : "v"(lo), "v"(hi)); return r; }
;     __device__ __forceinline__ void operator()(const f32x4 (&acc)[2][2][4][2], const Unit& u, int wr, int wc, int fr, int fq, const float (&rs)[2][4]) const {
;     ...
;                 for (int m = 0; m < 4; ++m) { const int row = row0 + ai * HALF + m * 16; f32x4 v0 = acc[ai][bj][m][0], v1 = acc[ai][bj][m][1];
;                     if (rope) { const float* cs = tab + ((size_t)(row & pmask) * 16 + i0) * 2; const f32x4 c01 = *(const f32x4*)cs, c23 = *(const f32x4*)(cs + 4);
;                         const f32x4 a = v0, b = v1;
;                         v0[0] = a[0] * c01[0] - a[1] * c01[1]; v0[1] = a[0] * c01[1] + a[1] * c01[0];
;                         v0[2] = a[2] * c01[2] - a[3] * c01[3]; v0[3] = a[2] * c01[3] + a[3] * c01[2];
;                         v1[0] = b[0] * c23[0] - b[1] * c23[1]; v1[1] = b[0] * c23[1] + b[1] * c23[0];
;                         v1[2] = b[2] * c23[2] - b[3] * c23[3]; v1[3] = b[2] * c23[3] + b[3] * c23[2]; }
;                     u32x4 w; w.x = cvt_pk_bf16(v0[0], v0[1]); w.y = cvt_pk_bf16(v0[2], v0[3]); w.z = cvt_pk_bf16(v1[0], v1[1]); w.w = cvt_pk_bf16(v1[2], v1[3]);
;                     *(u32x4*)(O + (size_t)row * 768 + cb) = w;
.LBB0_1770:
	s_or_b64 exec, exec, s[48:49]
	v_cvt_pk_bf16_f32 v94, v94, v95
	v_cvt_pk_bf16_f32 v95, v96, v97
	v_cvt_pk_bf16_f32 v96, v90, v91
	v_mad_i64_i32 v[90:91], s[0:1], v100, s91, v[152:153]
	v_cvt_pk_bf16_f32 v97, v92, v93
	global_store_dwordx4 v[90:91], v[94:97], off
	v_add_u32_e32 v92, 0x90, v158
	v_and_b32_e32 v90, s25, v92
	v_lshlrev_b32_e32 v90, 4, v90
	s_and_saveexec_b64 s[48:49], vcc
	s_cbranch_execz .LBB0_1772
	v_mov_b32_e32 v91, v81
	v_lshl_add_u64 v[94:95], v[150:151], 0, v[90:91]
	v_lshl_add_u64 v[102:103], v[94:95], 3, s[78:79]
	s_nop 0
	v_pk_mul_f32 v[118:119], v[82:83], v[226:227] op_sel:[1,1] op_sel_hi:[1,0]
	v_pk_mul_f32 v[112:113], v[86:87], v[230:231] op_sel:[1,1] op_sel_hi:[1,0]
	v_pk_mul_f32 v[110:111], v[86:87], v[230:231]
	v_pk_fma_f32 v[86:87], v[86:87], v[230:231], v[112:113] op_sel_hi:[0,1,1]
	v_mul_f32_e32 v86, v89, v233
	v_pk_fma_f32 v[102:103], v[88:89], v[232:233], v[86:87] op_sel_hi:[1,1,0] neg_lo:[0,0,1] neg_hi:[0,0,1]
	v_mul_f32_e32 v86, v89, v232
	v_pk_fma_f32 v[104:105], v[88:89], v[232:233], v[86:87] op_sel:[0,1,0] op_sel_hi:[1,0,0]
	v_pk_mul_f32 v[88:89], v[82:83], v[226:227]
	v_pk_fma_f32 v[82:83], v[82:83], v[226:227], v[118:119] op_sel_hi:[0,1,1]
	v_mul_f32_e32 v82, v85, v229
	v_pk_fma_f32 v[94:95], v[84:85], v[228:229], v[82:83] op_sel_hi:[1,1,0] neg_lo:[0,0,1] neg_hi:[0,0,1]
	v_mul_f32_e32 v82, v85, v228
	v_pk_fma_f32 v[96:97], v[84:85], v[228:229], v[82:83] op_sel:[0,1,0] op_sel_hi:[1,0,0]
	v_sub_f32_e32 v86, v110, v112
	v_sub_f32_e32 v82, v88, v118
	v_mov_b32_e32 v88, v102
	v_mov_b32_e32 v89, v104
	v_mov_b32_e32 v84, v94
	v_mov_b32_e32 v85, v96
.LBB0_1772:
	s_or_b64 exec, exec, s[48:49]
	v_cvt_pk_bf16_f32 v86, v86, v87
	v_cvt_pk_bf16_f32 v87, v88, v89
	v_cvt_pk_bf16_f32 v88, v82, v83
	v_mad_i64_i32 v[82:83], s[0:1], v92, s91, v[152:153]
	v_cvt_pk_bf16_f32 v89, v84, v85
	global_store_dwordx4 v[82:83], v[86:89], off
	v_add_u32_e32 v84, 0xa0, v158
	v_and_b32_e32 v82, s25, v84
	v_lshlrev_b32_e32 v82, 4, v82
	s_and_saveexec_b64 s[48:49], vcc
	s_cbranch_execz .LBB0_1774
	v_mov_b32_e32 v83, v81
	v_lshl_add_u64 v[86:87], v[150:151], 0, v[82:83]
	v_lshl_add_u64 v[94:95], v[86:87], 3, s[78:79]
	s_nop 0
	v_pk_mul_f32 v[110:111], v[72:73], v[234:235] op_sel:[1,1] op_sel_hi:[1,0]
	v_pk_mul_f32 v[104:105], v[76:77], v[238:239] op_sel:[1,1] op_sel_hi:[1,0]
	v_pk_mul_f32 v[102:103], v[76:77], v[238:239]
	v_pk_fma_f32 v[76:77], v[76:77], v[238:239], v[104:105] op_sel_hi:[0,1,1]
	v_mul_f32_e32 v76, v79, v241
	v_pk_fma_f32 v[94:95], v[78:79], v[240:241], v[76:77] op_sel_hi:[1,1,0] neg_lo:[0,0,1] neg_hi:[0,0,1]
	v_mul_f32_e32 v76, v79, v240
	v_pk_fma_f32 v[96:97], v[78:79], v[240:241], v[76:77] op_sel:[0,1,0] op_sel_hi:[1,0,0]
	v_pk_mul_f32 v[78:79], v[72:73], v[234:235]
	v_pk_fma_f32 v[72:73], v[72:73], v[234:235], v[110:111] op_sel_hi:[0,1,1]
	v_mul_f32_e32 v72, v75, v237
	v_pk_fma_f32 v[86:87], v[74:75], v[236:237], v[72:73] op_sel_hi:[1,1,0] neg_lo:[0,0,1] neg_hi:[0,0,1]
	v_mul_f32_e32 v72, v75, v236
	v_pk_fma_f32 v[88:89], v[74:75], v[236:237], v[72:73] op_sel:[0,1,0] op_sel_hi:[1,0,0]
	v_sub_f32_e32 v76, v102, v104
	v_sub_f32_e32 v72, v78, v110
	v_mov_b32_e32 v78, v94
	v_mov_b32_e32 v79, v96
	v_mov_b32_e32 v74, v86
	v_mov_b32_e32 v75, v88
.LBB0_1774:
	s_or_b64 exec, exec, s[48:49]
	v_cvt_pk_bf16_f32 v76, v76, v77
	v_cvt_pk_bf16_f32 v77, v78, v79
	v_cvt_pk_bf16_f32 v78, v72, v73
	v_mad_i64_i32 v[72:73], s[0:1], v84, s91, v[152:153]
	v_cvt_pk_bf16_f32 v79, v74, v75
	global_store_dwordx4 v[72:73], v[76:79], off
	v_add_u32_e32 v74, 0xb0, v158
	v_and_b32_e32 v72, s25, v74
	v_lshlrev_b32_e32 v72, 4, v72
	s_and_saveexec_b64 s[48:49], vcc
	s_cbranch_execz .LBB0_1776
	v_mov_b32_e32 v73, v81
	v_lshl_add_u64 v[76:77], v[150:151], 0, v[72:73]
	v_lshl_add_u64 v[86:87], v[76:77], 3, s[78:79]
	s_nop 0
	v_pk_mul_f32 v[102:103], v[64:65], v[242:243] op_sel:[1,1] op_sel_hi:[1,0]
	v_pk_mul_f32 v[96:97], v[68:69], v[246:247] op_sel:[1,1] op_sel_hi:[1,0]
	v_pk_mul_f32 v[94:95], v[68:69], v[246:247]
	v_pk_fma_f32 v[68:69], v[68:69], v[246:247], v[96:97] op_sel_hi:[0,1,1]
	v_mul_f32_e32 v68, v71, v249
	v_pk_fma_f32 v[86:87], v[70:71], v[248:249], v[68:69] op_sel_hi:[1,1,0] neg_lo:[0,0,1] neg_hi:[0,0,1]
	v_mul_f32_e32 v68, v71, v248
	v_pk_fma_f32 v[88:89], v[70:71], v[248:249], v[68:69] op_sel:[0,1,0] op_sel_hi:[1,0,0]
	v_pk_mul_f32 v[70:71], v[64:65], v[242:243]
	v_pk_fma_f32 v[64:65], v[64:65], v[242:243], v[102:103] op_sel_hi:[0,1,1]
	v_mul_f32_e32 v64, v67, v245
	v_pk_fma_f32 v[76:77], v[66:67], v[244:245], v[64:65] op_sel_hi:[1,1,0] neg_lo:[0,0,1] neg_hi:[0,0,1]
	v_mul_f32_e32 v64, v67, v244
	v_pk_fma_f32 v[78:79], v[66:67], v[244:245], v[64:65] op_sel:[0,1,0] op_sel_hi:[1,0,0]
	v_sub_f32_e32 v68, v94, v96
	v_sub_f32_e32 v64, v70, v102
	v_mov_b32_e32 v70, v86
	v_mov_b32_e32 v71, v88
	v_mov_b32_e32 v66, v76
	v_mov_b32_e32 v67, v78
; __device__ __forceinline__ unsigned cvt_pk_bf16(float lo, float hi) { unsigned r; asm volatile("v_cvt_pk_bf16_f32 %0, %1, %2" : "=v"(r) : "v"(lo), "v"(hi)); return r; }
;     __device__ __forceinline__ void operator()(const f32x4 (&acc)[2][2][4][2], const Unit& u, int wr, int wc, int fr, int fq, const float (&rs)[2][4]) const {
;     ...
;         for (int bj = 0; bj < 2; ++bj) {
;             const int cb = u.pn * BM + bj * HALF + wc * 32 + 8 * fq; const int d = cb % 96; const bool rope = d >= 64; const int i0 = rope ? ((d - 64) >> 1) : 0;
; #pragma unroll
;             for (int ai = 0; ai < 2; ++ai)
; #pragma unroll
;                 for (int m = 0; m < 4; ++m) { const int row = row0 + ai * HALF + m * 16; f32x4 v0 = acc[ai][bj][m][0], v1 = acc[ai][bj][m][1];
;                     if (rope) { const float* cs = tab + ((size_t)(row & pmask) * 16 + i0) * 2; const f32x4 c01 = *(const f32x4*)cs, c23 = *(const f32x4*)(cs + 4);
;                         const f32x4 a = v0, b = v1;
;                         v0[0] = a[0] * c01[0] - a[1] * c01[1]; v0[1] = a[0] * c01[1] + a[1] * c01[0];
;                         v0[2] = a[2] * c01[2] - a[3] * c01[3]; v0[3] = a[2] * c01[3] + a[3] * c01[2];
;                         v1[0] = b[0] * c23[0] - b[1] * c23[1]; v1[1] = b[0] * c23[1] + b[1] * c23[0];
;                         v1[2] = b[2] * c23[2] - b[3] * c23[3]; v1[3] = b[2] * c23[3] + b[3] * c23[2]; }
;                     u32x4 w; w.x = cvt_pk_bf16(v0[0], v0[1]); w.y = cvt_pk_bf16(v0[2], v0[3]); w.z = cvt_pk_bf16(v1[0], v1[1]); w.w = cvt_pk_bf16(v1[2], v1[3]);
;                     *(u32x4*)(O + (size_t)row * 768 + cb) = w;
;                     asm volatile("" ::: "memory"); }
.LBB0_1776:
	s_or_b64 exec, exec, s[48:49]
	v_cvt_pk_bf16_f32 v68, v68, v69
	v_cvt_pk_bf16_f32 v69, v70, v71
	v_cvt_pk_bf16_f32 v70, v64, v65
	v_mad_i64_i32 v[64:65], s[0:1], v74, s91, v[152:153]
	v_cvt_pk_bf16_f32 v71, v66, v67
	v_add_u32_e32 v66, 0x80, v148
	s_mov_b32 s0, 0x2aaaaaab
	global_store_dwordx4 v[64:65], v[68:71], off
	v_mul_hi_i32 v64, v66, s0
	v_lshrrev_b32_e32 v65, 31, v64
	v_lshrrev_b32_e32 v64, 4, v64
	v_add_u32_e32 v64, v64, v65
	v_mul_lo_u32 v64, v64, s83
	v_sub_u32_e32 v64, v66, v64
	v_cmp_lt_i32_e32 vcc, 63, v64
	v_subrev_u32_e32 v64, 64, v64
	v_ashrrev_i32_e32 v64, 1, v64
	v_ashrrev_i32_e32 v65, 31, v64
	s_and_saveexec_b64 s[48:49], vcc
	s_cbranch_execz .Lqr_h1
	v_and_b32_e32 v250, s25, v158
	v_lshlrev_b32_e32 v250, 4, v250
	v_mov_b32_e32 v251, v81
	v_lshl_add_u64 v[250:251], v[64:65], 0, v[250:251]
	v_lshl_add_u64 v[250:251], v[250:251], 3, s[78:79]
	global_load_dwordx4 v[186:189], v[250:251], off offset:16
	global_load_dwordx4 v[190:193], v[250:251], off
	v_add_u32_e32 v250, 16, v158
	v_and_b32_e32 v250, s25, v250
	v_lshlrev_b32_e32 v250, 4, v250
	v_mov_b32_e32 v251, v81
	v_lshl_add_u64 v[250:251], v[64:65], 0, v[250:251]
	v_lshl_add_u64 v[250:251], v[250:251], 3, s[78:79]
	global_load_dwordx4 v[194:197], v[250:251], off offset:16
	global_load_dwordx4 v[198:201], v[250:251], off
	v_add_u32_e32 v250, 32, v158
	v_and_b32_e32 v250, s25, v250
	v_lshlrev_b32_e32 v250, 4, v250
	v_mov_b32_e32 v251, v81
	v_lshl_add_u64 v[250:251], v[64:65], 0, v[250:251]
	v_lshl_add_u64 v[250:251], v[250:251], 3, s[78:79]
	global_load_dwordx4 v[202:205], v[250:251], off offset:16
	global_load_dwordx4 v[206:209], v[250:251], off
	v_add_u32_e32 v250, 48, v158
	v_and_b32_e32 v250, s25, v250
	v_lshlrev_b32_e32 v250, 4, v250
	v_mov_b32_e32 v251, v81
	v_lshl_add_u64 v[250:251], v[64:65], 0, v[250:251]
	v_lshl_add_u64 v[250:251], v[250:251], 3, s[78:79]
	global_load_dwordx4 v[210:213], v[250:251], off offset:16
	global_load_dwordx4 v[214:217], v[250:251], off
	v_add_u32_e32 v250, 0x80, v158
	v_and_b32_e32 v250, s25, v250
	v_lshlrev_b32_e32 v250, 4, v250
	v_mov_b32_e32 v251, v81
	v_lshl_add_u64 v[250:251], v[64:65], 0, v[250:251]
	v_lshl_add_u64 v[250:251], v[250:251], 3, s[78:79]
	global_load_dwordx4 v[218:221], v[250:251], off offset:16
	global_load_dwordx4 v[222:225], v[250:251], off
	v_add_u32_e32 v250, 0x90, v158
	v_and_b32_e32 v250, s25, v250
	v_lshlrev_b32_e32 v250, 4, v250
	v_mov_b32_e32 v251, v81
	v_lshl_add_u64 v[250:251], v[64:65], 0, v[250:251]
	v_lshl_add_u64 v[250:251], v[250:251], 3, s[78:79]
	global_load_dwordx4 v[226:229], v[250:251], off offset:16
	global_load_dwordx4 v[230:233], v[250:251], off
	v_add_u32_e32 v250, 0xa0, v158
	v_and_b32_e32 v250, s25, v250
	v_lshlrev_b32_e32 v250, 4, v250
	v_mov_b32_e32 v251, v81
	v_lshl_add_u64 v[250:251], v[64:65], 0, v[250:251]
	v_lshl_add_u64 v[250:251], v[250:251], 3, s[78:79]
	global_load_dwordx4 v[234:237], v[250:251], off offset:16
	global_load_dwordx4 v[238:241], v[250:251], off
	v_add_u32_e32 v250, 0xb0, v158
	v_and_b32_e32 v250, s25, v250
	v_lshlrev_b32_e32 v250, 4, v250
	v_mov_b32_e32 v251, v81
	v_lshl_add_u64 v[250:251], v[64:65], 0, v[250:251]
	v_lshl_add_u64 v[250:251], v[250:251], 3, s[78:79]
	global_load_dwordx4 v[242:245], v[250:251], off offset:16
	global_load_dwordx4 v[246:249], v[250:251], off
	s_waitcnt vmcnt(0)
.Lqr_h1:
	s_or_b64 exec, exec, s[48:49]
	s_and_saveexec_b64 s[48:49], vcc
	s_cbranch_execz .LBB0_1778
	v_lshl_add_u64 v[68:69], v[64:65], 0, v[80:81]
	v_lshl_add_u64 v[76:77], v[68:69], 3, s[78:79]
	s_nop 0
	v_pk_mul_f32 v[94:95], v[56:57], v[186:187] op_sel:[1,1] op_sel_hi:[1,0]
	v_pk_mul_f32 v[88:89], v[60:61], v[190:191] op_sel:[1,1] op_sel_hi:[1,0]
	v_pk_mul_f32 v[86:87], v[60:61], v[190:191]
	v_pk_fma_f32 v[60:61], v[60:61], v[190:191], v[88:89] op_sel_hi:[0,1,1]
	v_mul_f32_e32 v60, v63, v193
	v_pk_fma_f32 v[76:77], v[62:63], v[192:193], v[60:61] op_sel_hi:[1,1,0] neg_lo:[0,0,1] neg_hi:[0,0,1]
	v_mul_f32_e32 v60, v63, v192
	v_pk_fma_f32 v[78:79], v[62:63], v[192:193], v[60:61] op_sel:[0,1,0] op_sel_hi:[1,0,0]
	v_pk_mul_f32 v[62:63], v[56:57], v[186:187]
	v_pk_fma_f32 v[56:57], v[56:57], v[186:187], v[94:95] op_sel_hi:[0,1,1]
	v_mul_f32_e32 v56, v59, v189
	v_pk_fma_f32 v[68:69], v[58:59], v[188:189], v[56:57] op_sel_hi:[1,1,0] neg_lo:[0,0,1] neg_hi:[0,0,1]
	v_mul_f32_e32 v56, v59, v188
	v_pk_fma_f32 v[70:71], v[58:59], v[188:189], v[56:57] op_sel:[0,1,0] op_sel_hi:[1,0,0]
	v_sub_f32_e32 v60, v86, v88
	v_sub_f32_e32 v56, v62, v94
	v_mov_b32_e32 v62, v76
	v_mov_b32_e32 v63, v78
	v_mov_b32_e32 v58, v68
	v_mov_b32_e32 v59, v70
.LBB0_1778:
	s_or_b64 exec, exec, s[48:49]
	v_ashrrev_i32_e32 v67, 31, v66
	v_mad_i64_i32 v[68:69], s[0:1], v158, s91, 0
	v_lshl_add_u64 v[66:67], v[66:67], 1, s[56:57]
	v_cvt_pk_bf16_f32 v60, v60, v61
	v_cvt_pk_bf16_f32 v61, v62, v63
	v_cvt_pk_bf16_f32 v62, v56, v57
	v_lshl_add_u64 v[56:57], v[66:67], 0, v[68:69]
	v_cvt_pk_bf16_f32 v63, v58, v59
	global_store_dwordx4 v[56:57], v[60:63], off
	s_and_saveexec_b64 s[48:49], vcc
	s_cbranch_execz .LBB0_1780
	v_mov_b32_e32 v123, v81
	v_lshl_add_u64 v[56:57], v[64:65], 0, v[122:123]
	v_lshl_add_u64 v[60:61], v[56:57], 3, s[78:79]
	s_nop 0
	v_pk_mul_f32 v[76:77], v[48:49], v[194:195] op_sel:[1,1] op_sel_hi:[1,0]
	v_pk_mul_f32 v[70:71], v[52:53], v[198:199] op_sel:[1,1] op_sel_hi:[1,0]
	v_pk_mul_f32 v[68:69], v[52:53], v[198:199]
	v_pk_fma_f32 v[52:53], v[52:53], v[198:199], v[70:71] op_sel_hi:[0,1,1]
	v_mul_f32_e32 v52, v55, v201
	v_pk_fma_f32 v[60:61], v[54:55], v[200:201], v[52:53] op_sel_hi:[1,1,0] neg_lo:[0,0,1] neg_hi:[0,0,1]
	v_mul_f32_e32 v52, v55, v200
	v_pk_fma_f32 v[62:63], v[54:55], v[200:201], v[52:53] op_sel:[0,1,0] op_sel_hi:[1,0,0]
	v_pk_mul_f32 v[54:55], v[48:49], v[194:195]
	v_pk_fma_f32 v[48:49], v[48:49], v[194:195], v[76:77] op_sel_hi:[0,1,1]
	v_mul_f32_e32 v48, v51, v197
	v_pk_fma_f32 v[56:57], v[50:51], v[196:197], v[48:49] op_sel_hi:[1,1,0] neg_lo:[0,0,1] neg_hi:[0,0,1]
	v_mul_f32_e32 v48, v51, v196
	v_pk_fma_f32 v[58:59], v[50:51], v[196:197], v[48:49] op_sel:[0,1,0] op_sel_hi:[1,0,0]
	v_sub_f32_e32 v52, v68, v70
	v_sub_f32_e32 v48, v54, v76
	v_mov_b32_e32 v54, v60
	v_mov_b32_e32 v55, v62
	v_mov_b32_e32 v50, v56
	v_mov_b32_e32 v51, v58
; __device__ __forceinline__ unsigned cvt_pk_bf16(float lo, float hi) { unsigned r; asm volatile("v_cvt_pk_bf16_f32 %0, %1, %2" : "=v"(r) : "v"(lo), "v"(hi)); return r; }
;     __device__ __forceinline__ void operator()(const f32x4 (&acc)[2][2][4][2], const Unit& u, int wr, int wc, int fr, int fq, const float (&rs)[2][4]) const {
;     ...
;             for (int ai = 0; ai < 2; ++ai)
; #pragma unroll
;                 for (int m = 0; m < 4; ++m) { const int row = row0 + ai * HALF + m * 16; f32x4 v0 = acc[ai][bj][m][0], v1 = acc[ai][bj][m][1];
;                     if (rope) { const float* cs = tab + ((size_t)(row & pmask) * 16 + i0) * 2; const f32x4 c01 = *(const f32x4*)cs, c23 = *(const f32x4*)(cs + 4);
;                         const f32x4 a = v0, b = v1;
;                         v0[0] = a[0] * c01[0] - a[1] * c01[1]; v0[1] = a[0] * c01[1] + a[1] * c01[0];
;                         v0[2] = a[2] * c01[2] - a[3] * c01[3]; v0[3] = a[2] * c01[3] + a[3] * c01[2];
;                         v1[0] = b[0] * c23[0] - b[1] * c23[1]; v1[1] = b[0] * c23[1] + b[1] * c23[0];
;                         v1[2] = b[2] * c23[2] - b[3] * c23[3]; v1[3] = b[2] * c23[3] + b[3] * c23[2]; }
;                     u32x4 w; w.x = cvt_pk_bf16(v0[0], v0[1]); w.y = cvt_pk_bf16(v0[2], v0[3]); w.z = cvt_pk_bf16(v1[0], v1[1]); w.w = cvt_pk_bf16(v1[2], v1[3]);
;                     *(u32x4*)(O + (size_t)row * 768 + cb) = w;
;                     asm volatile("" ::: "memory"); }
.LBB0_1780:
	s_or_b64 exec, exec, s[48:49]
	v_mad_i64_i32 v[56:57], s[0:1], v124, s91, 0
	v_cvt_pk_bf16_f32 v52, v52, v53
	v_cvt_pk_bf16_f32 v53, v54, v55
	v_cvt_pk_bf16_f32 v54, v48, v49
	v_lshl_add_u64 v[48:49], v[66:67], 0, v[56:57]
	v_cvt_pk_bf16_f32 v55, v50, v51
	global_store_dwordx4 v[48:49], v[52:55], off
	s_and_saveexec_b64 s[48:49], vcc
	s_cbranch_execz .LBB0_1782
	v_mov_b32_e32 v115, v81
	v_lshl_add_u64 v[48:49], v[64:65], 0, v[114:115]
	v_lshl_add_u64 v[52:53], v[48:49], 3, s[78:79]
	s_nop 0
	v_pk_mul_f32 v[60:61], v[40:41], v[202:203] op_sel:[1,1] op_sel_hi:[1,0]
	v_pk_mul_f32 v[58:59], v[44:45], v[206:207] op_sel:[1,1] op_sel_hi:[1,0]
	v_pk_mul_f32 v[56:57], v[44:45], v[206:207]
	v_pk_fma_f32 v[44:45], v[44:45], v[206:207], v[58:59] op_sel_hi:[0,1,1]
	v_mul_f32_e32 v44, v47, v209
	v_pk_fma_f32 v[52:53], v[46:47], v[208:209], v[44:45] op_sel_hi:[1,1,0] neg_lo:[0,0,1] neg_hi:[0,0,1]
	v_mul_f32_e32 v44, v47, v208
	v_pk_fma_f32 v[54:55], v[46:47], v[208:209], v[44:45] op_sel:[0,1,0] op_sel_hi:[1,0,0]
	v_pk_mul_f32 v[46:47], v[40:41], v[202:203]
	v_pk_fma_f32 v[40:41], v[40:41], v[202:203], v[60:61] op_sel_hi:[0,1,1]
	v_mul_f32_e32 v40, v43, v205
	v_pk_fma_f32 v[48:49], v[42:43], v[204:205], v[40:41] op_sel_hi:[1,1,0] neg_lo:[0,0,1] neg_hi:[0,0,1]
	v_mul_f32_e32 v40, v43, v204
	v_pk_fma_f32 v[50:51], v[42:43], v[204:205], v[40:41] op_sel:[0,1,0] op_sel_hi:[1,0,0]
	v_sub_f32_e32 v44, v56, v58
	v_sub_f32_e32 v40, v46, v60
	v_mov_b32_e32 v46, v52
	v_mov_b32_e32 v47, v54
	v_mov_b32_e32 v42, v48
	v_mov_b32_e32 v43, v50
.LBB0_1782:
	s_or_b64 exec, exec, s[48:49]
	v_mad_i64_i32 v[48:49], s[0:1], v116, s91, 0
	v_cvt_pk_bf16_f32 v44, v44, v45
	v_cvt_pk_bf16_f32 v45, v46, v47
	v_cvt_pk_bf16_f32 v46, v40, v41
	v_lshl_add_u64 v[40:41], v[66:67], 0, v[48:49]
	v_cvt_pk_bf16_f32 v47, v42, v43
	global_store_dwordx4 v[40:41], v[44:47], off
	s_and_saveexec_b64 s[48:49], vcc
	s_cbranch_execz .LBB0_1784
	v_mov_b32_e32 v107, v81
	v_lshl_add_u64 v[40:41], v[64:65], 0, v[106:107]
	v_lshl_add_u64 v[44:45], v[40:41], 3, s[78:79]
	s_nop 0
	v_pk_mul_f32 v[52:53], v[32:33], v[210:211] op_sel:[1,1] op_sel_hi:[1,0]
	v_pk_mul_f32 v[50:51], v[36:37], v[214:215] op_sel:[1,1] op_sel_hi:[1,0]
	v_pk_mul_f32 v[48:49], v[36:37], v[214:215]
	v_pk_fma_f32 v[36:37], v[36:37], v[214:215], v[50:51] op_sel_hi:[0,1,1]
	v_mul_f32_e32 v36, v39, v217
	v_pk_fma_f32 v[44:45], v[38:39], v[216:217], v[36:37] op_sel_hi:[1,1,0] neg_lo:[0,0,1] neg_hi:[0,0,1]
	v_mul_f32_e32 v36, v39, v216
	v_pk_fma_f32 v[46:47], v[38:39], v[216:217], v[36:37] op_sel:[0,1,0] op_sel_hi:[1,0,0]
	v_pk_mul_f32 v[38:39], v[32:33], v[210:211]
	v_pk_fma_f32 v[32:33], v[32:33], v[210:211], v[52:53] op_sel_hi:[0,1,1]
	v_mul_f32_e32 v32, v35, v213
	v_pk_fma_f32 v[40:41], v[34:35], v[212:213], v[32:33] op_sel_hi:[1,1,0] neg_lo:[0,0,1] neg_hi:[0,0,1]
	v_mul_f32_e32 v32, v35, v212
	v_pk_fma_f32 v[42:43], v[34:35], v[212:213], v[32:33] op_sel:[0,1,0] op_sel_hi:[1,0,0]
	v_sub_f32_e32 v36, v48, v50
	v_sub_f32_e32 v32, v38, v52
	v_mov_b32_e32 v38, v44
	v_mov_b32_e32 v39, v46
	v_mov_b32_e32 v34, v40
	v_mov_b32_e32 v35, v42
.LBB0_1784:
	s_or_b64 exec, exec, s[48:49]
	v_mad_i64_i32 v[40:41], s[0:1], v108, s91, 0
	v_cvt_pk_bf16_f32 v36, v36, v37
	v_cvt_pk_bf16_f32 v37, v38, v39
	v_cvt_pk_bf16_f32 v38, v32, v33
	v_lshl_add_u64 v[32:33], v[66:67], 0, v[40:41]
	v_cvt_pk_bf16_f32 v39, v34, v35
	global_store_dwordx4 v[32:33], v[36:39], off
	s_and_saveexec_b64 s[48:49], vcc
	s_cbranch_execz .LBB0_1786
	v_mov_b32_e32 v99, v81
	v_lshl_add_u64 v[32:33], v[64:65], 0, v[98:99]
	v_lshl_add_u64 v[36:37], v[32:33], 3, s[78:79]
	s_nop 0
	v_pk_mul_f32 v[44:45], v[24:25], v[218:219] op_sel:[1,1] op_sel_hi:[1,0]
	v_pk_mul_f32 v[42:43], v[28:29], v[222:223] op_sel:[1,1] op_sel_hi:[1,0]
	v_pk_mul_f32 v[40:41], v[28:29], v[222:223]
	v_pk_fma_f32 v[28:29], v[28:29], v[222:223], v[42:43] op_sel_hi:[0,1,1]
	v_mul_f32_e32 v28, v31, v225
	v_pk_fma_f32 v[36:37], v[30:31], v[224:225], v[28:29] op_sel_hi:[1,1,0] neg_lo:[0,0,1] neg_hi:[0,0,1]
	v_mul_f32_e32 v28, v31, v224
	v_pk_fma_f32 v[38:39], v[30:31], v[224:225], v[28:29] op_sel:[0,1,0] op_sel_hi:[1,0,0]
	v_pk_mul_f32 v[30:31], v[24:25], v[218:219]
	v_pk_fma_f32 v[24:25], v[24:25], v[218:219], v[44:45] op_sel_hi:[0,1,1]
	v_mul_f32_e32 v24, v27, v221
	v_pk_fma_f32 v[32:33], v[26:27], v[220:221], v[24:25] op_sel_hi:[1,1,0] neg_lo:[0,0,1] neg_hi:[0,0,1]
	v_mul_f32_e32 v24, v27, v220
	v_pk_fma_f32 v[34:35], v[26:27], v[220:221], v[24:25] op_sel:[0,1,0] op_sel_hi:[1,0,0]
	v_sub_f32_e32 v28, v40, v42
	v_sub_f32_e32 v24, v30, v44
	v_mov_b32_e32 v30, v36
	v_mov_b32_e32 v31, v38
	v_mov_b32_e32 v26, v32
	v_mov_b32_e32 v27, v34
; __device__ __forceinline__ unsigned cvt_pk_bf16(float lo, float hi) { unsigned r; asm volatile("v_cvt_pk_bf16_f32 %0, %1, %2" : "=v"(r) : "v"(lo), "v"(hi)); return r; }
;     __device__ __forceinline__ void operator()(const f32x4 (&acc)[2][2][4][2], const Unit& u, int wr, int wc, int fr, int fq, const float (&rs)[2][4]) const {
;     ...
;             for (int ai = 0; ai < 2; ++ai)
; #pragma unroll
;                 for (int m = 0; m < 4; ++m) { const int row = row0 + ai * HALF + m * 16; f32x4 v0 = acc[ai][bj][m][0], v1 = acc[ai][bj][m][1];
;                     if (rope) { const float* cs = tab + ((size_t)(row & pmask) * 16 + i0) * 2; const f32x4 c01 = *(const f32x4*)cs, c23 = *(const f32x4*)(cs + 4);
;                         const f32x4 a = v0, b = v1;
;                         v0[0] = a[0] * c01[0] - a[1] * c01[1]; v0[1] = a[0] * c01[1] + a[1] * c01[0];
;                         v0[2] = a[2] * c01[2] - a[3] * c01[3]; v0[3] = a[2] * c01[3] + a[3] * c01[2];
;                         v1[0] = b[0] * c23[0] - b[1] * c23[1]; v1[1] = b[0] * c23[1] + b[1] * c23[0];
;                         v1[2] = b[2] * c23[2] - b[3] * c23[3]; v1[3] = b[2] * c23[3] + b[3] * c23[2]; }
;                     u32x4 w; w.x = cvt_pk_bf16(v0[0], v0[1]); w.y = cvt_pk_bf16(v0[2], v0[3]); w.z = cvt_pk_bf16(v1[0], v1[1]); w.w = cvt_pk_bf16(v1[2], v1[3]);
;                     *(u32x4*)(O + (size_t)row * 768 + cb) = w;
;                     asm volatile("" ::: "memory"); }
.LBB0_1786:
	s_or_b64 exec, exec, s[48:49]
	v_mad_i64_i32 v[32:33], s[0:1], v100, s91, 0
	v_cvt_pk_bf16_f32 v28, v28, v29
	v_cvt_pk_bf16_f32 v29, v30, v31
	v_cvt_pk_bf16_f32 v30, v24, v25
	v_lshl_add_u64 v[24:25], v[66:67], 0, v[32:33]
	v_cvt_pk_bf16_f32 v31, v26, v27
	global_store_dwordx4 v[24:25], v[28:31], off
	s_and_saveexec_b64 s[48:49], vcc
	s_cbranch_execz .LBB0_1788
	v_mov_b32_e32 v91, v81
	v_lshl_add_u64 v[24:25], v[64:65], 0, v[90:91]
	v_lshl_add_u64 v[28:29], v[24:25], 3, s[78:79]
	s_nop 0
	v_pk_mul_f32 v[36:37], v[16:17], v[226:227] op_sel:[1,1] op_sel_hi:[1,0]
	v_pk_mul_f32 v[34:35], v[20:21], v[230:231] op_sel:[1,1] op_sel_hi:[1,0]
	v_pk_mul_f32 v[32:33], v[20:21], v[230:231]
	v_pk_fma_f32 v[20:21], v[20:21], v[230:231], v[34:35] op_sel_hi:[0,1,1]
	v_mul_f32_e32 v20, v23, v233
	v_pk_fma_f32 v[28:29], v[22:23], v[232:233], v[20:21] op_sel_hi:[1,1,0] neg_lo:[0,0,1] neg_hi:[0,0,1]
	v_mul_f32_e32 v20, v23, v232
	v_pk_fma_f32 v[30:31], v[22:23], v[232:233], v[20:21] op_sel:[0,1,0] op_sel_hi:[1,0,0]
	v_pk_mul_f32 v[22:23], v[16:17], v[226:227]
	v_pk_fma_f32 v[16:17], v[16:17], v[226:227], v[36:37] op_sel_hi:[0,1,1]
	v_mul_f32_e32 v16, v19, v229
	v_pk_fma_f32 v[24:25], v[18:19], v[228:229], v[16:17] op_sel_hi:[1,1,0] neg_lo:[0,0,1] neg_hi:[0,0,1]
	v_mul_f32_e32 v16, v19, v228
	v_pk_fma_f32 v[26:27], v[18:19], v[228:229], v[16:17] op_sel:[0,1,0] op_sel_hi:[1,0,0]
	v_sub_f32_e32 v20, v32, v34
	v_sub_f32_e32 v16, v22, v36
	v_mov_b32_e32 v22, v28
	v_mov_b32_e32 v23, v30
	v_mov_b32_e32 v18, v24
	v_mov_b32_e32 v19, v26
.LBB0_1788:
	s_or_b64 exec, exec, s[48:49]
	v_mad_i64_i32 v[24:25], s[0:1], v92, s91, 0
	v_cvt_pk_bf16_f32 v20, v20, v21
	v_cvt_pk_bf16_f32 v21, v22, v23
	v_cvt_pk_bf16_f32 v22, v16, v17
	v_lshl_add_u64 v[16:17], v[66:67], 0, v[24:25]
	v_cvt_pk_bf16_f32 v23, v18, v19
	global_store_dwordx4 v[16:17], v[20:23], off
	s_and_saveexec_b64 s[48:49], vcc
	s_cbranch_execz .LBB0_1790
	v_mov_b32_e32 v83, v81
	v_lshl_add_u64 v[16:17], v[64:65], 0, v[82:83]
	v_lshl_add_u64 v[20:21], v[16:17], 3, s[78:79]
	s_nop 0
	v_pk_mul_f32 v[28:29], v[8:9], v[234:235] op_sel:[1,1] op_sel_hi:[1,0]
	v_pk_mul_f32 v[26:27], v[12:13], v[238:239] op_sel:[1,1] op_sel_hi:[1,0]
	v_pk_mul_f32 v[24:25], v[12:13], v[238:239]
	v_pk_fma_f32 v[12:13], v[12:13], v[238:239], v[26:27] op_sel_hi:[0,1,1]
	v_mul_f32_e32 v12, v15, v241
	v_pk_fma_f32 v[20:21], v[14:15], v[240:241], v[12:13] op_sel_hi:[1,1,0] neg_lo:[0,0,1] neg_hi:[0,0,1]
	v_mul_f32_e32 v12, v15, v240
	v_pk_fma_f32 v[22:23], v[14:15], v[240:241], v[12:13] op_sel:[0,1,0] op_sel_hi:[1,0,0]
	v_pk_mul_f32 v[14:15], v[8:9], v[234:235]
	v_pk_fma_f32 v[8:9], v[8:9], v[234:235], v[28:29] op_sel_hi:[0,1,1]
	v_mul_f32_e32 v8, v11, v237
	v_pk_fma_f32 v[16:17], v[10:11], v[236:237], v[8:9] op_sel_hi:[1,1,0] neg_lo:[0,0,1] neg_hi:[0,0,1]
	v_mul_f32_e32 v8, v11, v236
	v_pk_fma_f32 v[18:19], v[10:11], v[236:237], v[8:9] op_sel:[0,1,0] op_sel_hi:[1,0,0]
	v_sub_f32_e32 v12, v24, v26
	v_sub_f32_e32 v8, v14, v28
	v_mov_b32_e32 v14, v20
	v_mov_b32_e32 v15, v22
	v_mov_b32_e32 v10, v16
	v_mov_b32_e32 v11, v18
.LBB0_1790:
	s_or_b64 exec, exec, s[48:49]
	v_mad_i64_i32 v[16:17], s[0:1], v84, s91, 0
	v_cvt_pk_bf16_f32 v12, v12, v13
	v_cvt_pk_bf16_f32 v13, v14, v15
	v_cvt_pk_bf16_f32 v14, v8, v9
	v_lshl_add_u64 v[8:9], v[66:67], 0, v[16:17]
	v_cvt_pk_bf16_f32 v15, v10, v11
	global_store_dwordx4 v[8:9], v[12:15], off
	s_and_saveexec_b64 s[48:49], vcc
	s_cbranch_execz .LBB0_1792
	v_mov_b32_e32 v73, v81
	v_lshl_add_u64 v[8:9], v[64:65], 0, v[72:73]
	v_lshl_add_u64 v[12:13], v[8:9], 3, s[78:79]
	s_nop 0
	v_pk_mul_f32 v[20:21], v[0:1], v[242:243] op_sel:[1,1] op_sel_hi:[1,0]
	v_pk_mul_f32 v[18:19], v[4:5], v[246:247] op_sel:[1,1] op_sel_hi:[1,0]
	v_pk_mul_f32 v[16:17], v[4:5], v[246:247]
	v_pk_fma_f32 v[4:5], v[4:5], v[246:247], v[18:19] op_sel_hi:[0,1,1]
	v_mul_f32_e32 v4, v7, v249
	v_pk_fma_f32 v[12:13], v[6:7], v[248:249], v[4:5] op_sel_hi:[1,1,0] neg_lo:[0,0,1] neg_hi:[0,0,1]
	v_mul_f32_e32 v4, v7, v248
	v_pk_fma_f32 v[14:15], v[6:7], v[248:249], v[4:5] op_sel:[0,1,0] op_sel_hi:[1,0,0]
	v_pk_mul_f32 v[6:7], v[0:1], v[242:243]
	v_pk_fma_f32 v[0:1], v[0:1], v[242:243], v[20:21] op_sel_hi:[0,1,1]
	v_mul_f32_e32 v0, v3, v245
	v_pk_fma_f32 v[8:9], v[2:3], v[244:245], v[0:1] op_sel_hi:[1,1,0] neg_lo:[0,0,1] neg_hi:[0,0,1]
	v_mul_f32_e32 v0, v3, v244
	v_pk_fma_f32 v[10:11], v[2:3], v[244:245], v[0:1] op_sel:[0,1,0] op_sel_hi:[1,0,0]
	v_sub_f32_e32 v4, v16, v18
	v_sub_f32_e32 v0, v6, v20
	v_mov_b32_e32 v6, v12
	v_mov_b32_e32 v7, v14
	v_mov_b32_e32 v2, v8
	v_mov_b32_e32 v3, v10

; __device__ __forceinline__ float bf_lo(unsigned w) { return __uint_as_float(w << 16); }
; __device__ __forceinline__ float bf_hi(unsigned w) { return __uint_as_float(w & 0xffff0000u); }
; __global__ void __launch_bounds__(NTHREADS) mk_fwd(Params P) {
;     ...
;     BEGIN_PH {
;         const float* gn = P.in[I_FINAL_NORM];
;         f32x4 g4[4];
; #pragma unroll
;         for (int j = 0; j < 4; ++j) g4[j] = *((const f32x4*)gn + lane + 64 * j);
;         for (int m = gw; m < T; m += NGW) { const u32x2* xr = (const u32x2*)(XN + (size_t)m * DM) + lane; f32x4 v[4]; float s = 0.f;
; #pragma unroll
;             for (int j = 0; j < 4; ++j) { const u32x2 w = xr[64 * j]; v[j] = (f32x4){bf_lo(w.x), bf_hi(w.x), bf_lo(w.y), bf_hi(w.y)}; s += (v[j].x * v[j].x + v[j].y * v[j].y) + (v[j].z * v[j].z + v[j].w * v[j].w); }
;             const float rstd = rsqrtf(wave_sum(s) * (1.f / DM) + EPS);
;             f32x4* orow = (f32x4*)(out + (size_t)m * DM) + lane;
; #pragma unroll
;             for (int j = 0; j < 4; ++j) orow[64 * j] = v[j] * rstd * g4[j]; }
.LBB0_2127:
	s_cmp_ge_i32 s61, s88
	s_cselect_b64 s[0:1], -1, 0
	s_cmp_lt_i32 s61, s89
	s_cselect_b64 s[2:3], -1, 0
	s_and_b64 s[0:1], s[0:1], s[2:3]
	s_and_b64 vcc, exec, s[0:1]
	s_cbranch_vccz .LBB0_2199
	s_add_i32 s0, 0, 0x23fc8
	v_mov_b32_e32 v0, s0
	ds_read_b32 v0, v0
	s_add_i32 s0, 0, 0x23fcc
	s_waitcnt lgkmcnt(0)
	v_mov_b32_e32 v0, s0
	ds_read_b32 v0, v0
	v_readfirstlane_b32 s1, v167
	v_readlane_b32 s8, v254, 45
	v_readlane_b32 s9, v254, 46
	s_waitcnt lgkmcnt(0)
	v_readfirstlane_b32 s0, v0
	s_lshl_b32 s2, s0, 3
	s_and_b32 s3, s2, 0x7fff8
	s_ashr_i32 s2, s1, 6
	s_add_i32 s4, s3, s2
	s_cmpk_gt_i32 s4, 0x7fff
	s_cbranch_scc1 .LBB0_2131
	v_readlane_b32 s6, v253, 6
	v_readlane_b32 s7, v253, 7
	s_load_dwordx2 s[6:7], s[6:7], 0xc0
	v_and_b32_e32 v16, 63, v167
	v_lshlrev_b32_e32 v18, 4, v16
	s_and_b32 s5, s0, 0xffff
	s_ashr_i32 s3, s2, 31
	s_waitcnt lgkmcnt(0)
	global_load_dwordx4 v[0:3], v18, s[6:7]
	global_load_dwordx4 v[4:7], v18, s[6:7] offset:1024
	global_load_dwordx4 v[8:11], v18, s[6:7] offset:2048
	global_load_dwordx4 v[12:15], v18, s[6:7] offset:3072
	s_lshl_b32 s6, s5, 14
	s_lshl_b64 s[0:1], s[2:3], 11
	s_add_u32 s0, s6, s0
	s_addc_u32 s1, 0, s1
	v_mov_b32_e32 v19, 0
	s_add_u32 s0, s78, s0
	v_lshlrev_b32_e32 v16, 3, v16
	v_mov_b32_e32 v17, v19
	s_addc_u32 s1, s79, s1
	v_lshl_add_u64 v[16:17], s[0:1], 0, v[16:17]
	s_mov_b64 s[0:1], 0xaa00400
	s_ashr_i32 s9, s8, 31
	v_lshl_add_u64 v[16:17], v[16:17], 0, s[0:1]
	s_lshl_b64 s[0:1], s[8:9], 11
	s_lshl_b32 s5, s5, 15
	s_lshl_b64 s[2:3], s[2:3], 12
	s_add_u32 s2, s5, s2
	s_addc_u32 s3, 0, s3
	s_add_u32 s2, s76, s2
	s_addc_u32 s3, s77, s3
	v_lshl_add_u64 v[18:19], s[2:3], 0, v[18:19]
	s_mov_b64 s[2:3], 0x800
	v_lshl_add_u64 v[18:19], v[18:19], 0, s[2:3]
	s_lshl_b64 s[2:3], s[8:9], 12
	v_mov_b32_e32 v20, 0x358637bd
	s_mov_b32 s5, 0x800000
	global_load_dwordx2 v[46:47], v[16:17], off offset:-1024
	global_load_dwordx2 v[48:49], v[16:17], off offset:-512
	global_load_dwordx2 v[50:51], v[16:17], off
	global_load_dwordx2 v[52:53], v[16:17], off offset:512
	s_waitcnt vmcnt(0)
.LBB0_2130:
	v_lshlrev_b32_e32 v30, 16, v46
	v_and_b32_e32 v31, 0xffff0000, v46
	v_lshlrev_b32_e32 v22, 16, v47
	v_and_b32_e32 v23, 0xffff0000, v47
	v_lshlrev_b32_e32 v32, 16, v48
	v_and_b32_e32 v33, 0xffff0000, v48
	v_lshlrev_b32_e32 v24, 16, v49
	v_and_b32_e32 v25, 0xffff0000, v49
	v_lshlrev_b32_e32 v34, 16, v50
	v_and_b32_e32 v35, 0xffff0000, v50
	v_lshlrev_b32_e32 v26, 16, v51
	v_and_b32_e32 v27, 0xffff0000, v51
	v_mul_f32_e32 v21, v31, v31
	v_mul_f32_e32 v38, v23, v23
	v_mul_f32_e32 v39, v33, v33
	v_mul_f32_e32 v40, v25, v25
	v_lshlrev_b32_e32 v36, 16, v52
	v_and_b32_e32 v37, 0xffff0000, v52
	v_lshlrev_b32_e32 v28, 16, v53
	v_and_b32_e32 v29, 0xffff0000, v53
	s_add_i32 s4, s4, s8
	v_lshl_add_u64 v[16:17], v[16:17], 0, s[0:1]
	s_cmpk_gt_i32 s4, 0x7fff
	s_cbranch_scc1 .Lfn_skip
	global_load_dwordx2 v[46:47], v[16:17], off offset:-1024
	global_load_dwordx2 v[48:49], v[16:17], off offset:-512
	global_load_dwordx2 v[50:51], v[16:17], off
	global_load_dwordx2 v[52:53], v[16:17], off offset:512
.Lfn_skip:
	v_mul_f32_e32 v41, v35, v35
	v_mul_f32_e32 v42, v27, v27
	v_fmac_f32_e32 v21, v30, v30
	v_fmac_f32_e32 v38, v22, v22
	v_fmac_f32_e32 v39, v32, v32
	v_fmac_f32_e32 v40, v24, v24
	v_mul_f32_e32 v43, v37, v37
	v_mul_f32_e32 v44, v29, v29
	v_fmac_f32_e32 v41, v34, v34
	v_fmac_f32_e32 v42, v26, v26
	v_add_f32_e32 v21, v21, v38
	v_add_f32_e32 v38, v39, v40
	v_fmac_f32_e32 v43, v36, v36
	v_fmac_f32_e32 v44, v28, v28
	v_add_f32_e32 v39, v41, v42
	v_add_f32_e32 v21, v21, v38
	v_add_f32_e32 v40, v43, v44
	v_add_f32_e32 v21, v21, v39
	v_add_f32_e32 v21, v21, v40
	ds_swizzle_b32 v38, v21 offset:swizzle(SWAP,1)
	s_waitcnt lgkmcnt(0)
	v_add_f32_e32 v21, v21, v38
	ds_swizzle_b32 v38, v21 offset:swizzle(SWAP,2)
	s_waitcnt lgkmcnt(0)
	v_add_f32_e32 v21, v21, v38
	ds_swizzle_b32 v38, v21 offset:swizzle(SWAP,4)
	s_waitcnt lgkmcnt(0)
	v_add_f32_e32 v21, v21, v38
	ds_swizzle_b32 v38, v21 offset:swizzle(SWAP,8)
	s_waitcnt lgkmcnt(0)
	v_add_f32_e32 v21, v21, v38
	ds_swizzle_b32 v38, v21 offset:swizzle(SWAP,16)
	s_waitcnt lgkmcnt(0)
	v_add_f32_e32 v21, v21, v38
	v_mov_b32_e32 v38, v21
	s_nop 1
	v_permlane32_swap_b32_e32 v21, v38
	v_add_f32_e32 v21, v21, v38
	v_fmamk_f32 v21, v21, 0x3a800000, v20
	v_mul_f32_e32 v38, 0x4b800000, v21
	v_cmp_gt_f32_e32 vcc, s5, v21
	s_nop 1
	v_cndmask_b32_e32 v21, v21, v38, vcc
	v_rsq_f32_e32 v21, v21
	s_nop 0
	v_mul_f32_e32 v38, 0x45800000, v21
	v_cndmask_b32_e32 v38, v21, v38, vcc
	v_pk_mul_f32 v[30:31], v[38:39], v[30:31] op_sel_hi:[0,1]
	v_pk_mul_f32 v[22:23], v[38:39], v[22:23] op_sel_hi:[0,1]
	v_pk_mul_f32 v[32:33], v[38:39], v[32:33] op_sel_hi:[0,1]
	v_pk_mul_f32 v[40:41], v[38:39], v[24:25] op_sel_hi:[0,1]
	v_pk_mul_f32 v[34:35], v[38:39], v[34:35] op_sel_hi:[0,1]
	v_pk_mul_f32 v[42:43], v[38:39], v[26:27] op_sel_hi:[0,1]
	v_pk_mul_f32 v[44:45], v[38:39], v[36:37] op_sel_hi:[0,1]
	v_pk_mul_f32 v[36:37], v[38:39], v[28:29] op_sel_hi:[0,1]
	v_pk_mul_f32 v[24:25], v[22:23], v[2:3]
	v_pk_mul_f32 v[22:23], v[30:31], v[0:1]
	v_pk_mul_f32 v[28:29], v[40:41], v[6:7]
	v_pk_mul_f32 v[26:27], v[32:33], v[4:5]
	v_pk_mul_f32 v[32:33], v[42:43], v[10:11]
	v_pk_mul_f32 v[30:31], v[34:35], v[8:9]
	v_pk_mul_f32 v[36:37], v[36:37], v[14:15]
	v_pk_mul_f32 v[34:35], v[44:45], v[12:13]
	global_store_dwordx4 v[18:19], v[22:25], off offset:-2048
	global_store_dwordx4 v[18:19], v[26:29], off offset:-1024
	global_store_dwordx4 v[18:19], v[30:33], off
	global_store_dwordx4 v[18:19], v[34:37], off offset:1024
	v_lshl_add_u64 v[18:19], v[18:19], 0, s[2:3]
	s_waitcnt vmcnt(4)
	s_cbranch_scc0 .LBB0_2130
